# scan units get wave priorities via s_setprio: rwkv 2 > hgrn 1 > ssd 0 (rwkv unit was the critical path)
# speedup vs baseline: 1.0931x; 1.0638x over previous
.LBB0_316:
	s_setprio 0
	s_add_i32 s34, s34, s35
	s_cmpk_lt_i32 s34, 0x600
	s_cbranch_scc0 .LBB0_395
.LBB0_317:
	s_add_i32 s4, s34, 0xfffffd00
	s_cmpk_gt_i32 s34, 0x2ff
	s_cselect_b64 s[2:3], -1, 0
	s_and_b64 s[0:1], s[2:3], exec
	s_cselect_b32 s0, s4, s34
	s_mul_hi_i32 s33, s0, 0x55555556
	s_lshr_b32 s1, s33, 31
	s_add_i32 s33, s33, s1
	s_mul_i32 s1, s33, 3
	s_sub_i32 s24, s0, s1
	s_mov_b64 s[4:5], -1
	s_mov_b64 s[6:7], 0
	s_cmp_lt_i32 s24, 1
	s_mov_b64 s[0:1], 0
	s_cbranch_scc1 .LBB0_341
	s_cmp_eq_u32 s24, 1
	s_mov_b64 s[0:1], -1
	s_cbranch_scc0 .LBB0_352
	s_setprio 1
	s_ashr_i32 s25, s33, 5
	s_and_b64 s[0:1], s[2:3], exec
	s_cselect_b32 s0, 8, 0
	s_add_i32 s25, s25, s0
	s_cmp_lt_i32 s25, 8
	v_mov_b32_e32 v30, v148
	s_cselect_b64 s[8:9], -1, 0
	s_cmp_gt_i32 s25, 7
	s_mov_b64 s[0:1], -1
	s_cbranch_scc0 .LBB0_321
	s_lshl_b32 s0, s25, 6
	s_add_i32 s4, s0, 0x7e80
	s_mov_b64 s[0:1], 0

.LBB0_381:
	s_setprio 2
	s_ashr_i32 s4, s33, 5
	s_and_b64 s[0:1], s[2:3], exec
	s_cselect_b32 s0, 8, 0
	s_add_i32 s4, s4, s0
	s_cmp_lt_i32 s4, 8
	s_waitcnt vmcnt(0)
	v_mov_b32_e32 v11, v148
	s_cselect_b64 s[0:1], -1, 0
	s_cmp_gt_i32 s4, 7
	s_mov_b64 s[2:3], -1
	s_cbranch_scc0 .LBB0_383
	s_lshl_b32 s2, s4, 6
	s_add_i32 s8, s2, 0x7e80
	s_mov_b64 s[2:3], 0

.LBB0_1020:
	s_add_i32 s4, s34, 0xfffffd00
	s_cmpk_gt_i32 s34, 0x2ff
	s_cselect_b64 s[2:3], -1, 0
	s_and_b64 s[0:1], s[2:3], exec
	s_cselect_b32 s0, s4, s34
	s_mul_hi_i32 s33, s0, 0x55555556
	s_lshr_b32 s1, s33, 31
	s_add_i32 s33, s33, s1
	s_mul_i32 s1, s33, 3
	s_sub_i32 s24, s0, s1
	s_mov_b64 s[4:5], -1
	s_mov_b64 s[8:9], 0
	s_cmp_lt_i32 s24, 1
	s_mov_b64 s[0:1], 0
	s_cbranch_scc1 .LBB0_1044
	s_cmp_eq_u32 s24, 1
	s_mov_b64 s[0:1], -1
	s_cbranch_scc0 .LBB0_1055
	s_setprio 1
	s_ashr_i32 s25, s33, 5
	s_and_b64 s[0:1], s[2:3], exec
	s_cselect_b32 s0, 8, 0
	s_add_i32 s25, s25, s0
	s_cmp_lt_i32 s25, 8
	v_mov_b32_e32 v30, v148
	s_cselect_b64 s[10:11], -1, 0
	s_cmp_gt_i32 s25, 7
	s_mov_b64 s[0:1], -1
	s_cbranch_scc0 .LBB0_1024
	s_lshl_b32 s0, s25, 6
	s_add_i32 s4, s0, 0x7e80
	s_mov_b64 s[0:1], 0

.LBB0_1084:
	s_setprio 2
	s_ashr_i32 s4, s33, 5
	s_and_b64 s[0:1], s[2:3], exec
	s_cselect_b32 s0, 8, 0
	s_add_i32 s4, s4, s0
	s_cmp_lt_i32 s4, 8
	s_waitcnt vmcnt(0)
	v_mov_b32_e32 v11, v148
	s_cselect_b64 s[0:1], -1, 0
	s_cmp_gt_i32 s4, 7
	s_mov_b64 s[2:3], -1
	s_cbranch_scc0 .LBB0_1086
	s_lshl_b32 s2, s4, 6
	s_add_i32 s10, s2, 0x7e80
	s_mov_b64 s[2:3], 0
